# EpiResid epilogue (P6,P11): batch 16 residual loads instead of 32 serialized load-wait-store round trips
# baseline (speedup 1.0000x reference)
;   DI void operator()(const f32x16 (&acc)[2][4], int mbase, int nbase, int l32, int g) const {
; #pragma unroll
;     for (int nb = 0; nb < 2; ++nb)
; #pragma unroll
;       for (int mb = 0; mb < 4; ++mb) {
;         const size_t tok = mbase + 32 * mb + l32;
; #pragma unroll
;         for (int j = 0; j < 4; ++j) {
;           const int n = nbase + 32 * nb + 8 * j + 4 * g;
;           f32x4 r = *(const f32x4*)(R + tok * D + n);
;           r[0] += acc[nb][mb][4 * j]; r[1] += acc[nb][mb][4 * j + 1]; r[2] += acc[nb][mb][4 * j + 2]; r[3] += acc[nb][mb][4 * j + 3];
;           *(f32x4*)(O + tok * D + n) = r;
;         }
.LBB0_744:
	s_and_b32 s12, s11, 0xc0
	s_ashr_i32 s11, s11, 1
	s_and_b32 s11, s11, 0xffffff80
	s_add_i32 s11, s11, s39
	v_lshrrev_b32_e32 v160, 3, v190
	v_and_or_b32 v168, v190, 31, s11
	v_and_or_b32 v160, v160, 4, s12
	v_or_b32_e32 v160, s10, v160
	s_mov_b64 s[2:3], s[68:69]
	v_lshlrev_b32_e32 v168, 13, v168
	v_lshl_add_u32 v244, v160, 2, v168
	v_add_u32_e32 v245, 0x40000, v244
	v_add_u32_e32 v246, 0x80000, v244
	v_add_u32_e32 v247, 0xc0000, v244
	s_add_i32 s26, s26, s27
	s_add_i32 s28, s28, s29
	s_mov_b64 s[12:13], -1
	global_load_dwordx4 v[160:163], v244, s[2:3]
	global_load_dwordx4 v[164:167], v244, s[2:3] offset:32
	global_load_dwordx4 v[168:171], v244, s[2:3] offset:64
	global_load_dwordx4 v[172:175], v244, s[2:3] offset:96
	global_load_dwordx4 v[176:179], v244, s[2:3] offset:128
	global_load_dwordx4 v[180:183], v244, s[2:3] offset:160
	global_load_dwordx4 v[186:189], v244, s[2:3] offset:192
	global_load_dwordx4 v[192:195], v244, s[2:3] offset:224
	global_load_dwordx4 v[200:203], v245, s[2:3]
	global_load_dwordx4 v[208:211], v245, s[2:3] offset:32
	global_load_dwordx4 v[212:215], v245, s[2:3] offset:64
	global_load_dwordx4 v[216:219], v245, s[2:3] offset:96
	global_load_dwordx4 v[220:223], v245, s[2:3] offset:128
	global_load_dwordx4 v[224:227], v245, s[2:3] offset:160
	global_load_dwordx4 v[228:231], v245, s[2:3] offset:192
	global_load_dwordx4 v[232:235], v245, s[2:3] offset:224
	global_load_dwordx4 v[236:239], v246, s[2:3]
	global_load_dwordx4 v[240:243], v246, s[2:3] offset:32
	s_waitcnt vmcnt(17)
	v_pk_add_f32 v[112:113], v[112:113], v[160:161]
	v_pk_add_f32 v[114:115], v[114:115], v[162:163]
	global_store_dwordx4 v244, v[112:115], s[20:21]
	global_load_dwordx4 v[160:163], v246, s[2:3] offset:64
	s_waitcnt vmcnt(18)
	v_pk_add_f32 v[116:117], v[116:117], v[164:165]
	v_pk_add_f32 v[118:119], v[118:119], v[166:167]
	global_store_dwordx4 v244, v[116:119], s[20:21] offset:32
	global_load_dwordx4 v[164:167], v246, s[2:3] offset:96
	s_waitcnt vmcnt(19)
	v_pk_add_f32 v[120:121], v[120:121], v[168:169]
	v_pk_add_f32 v[122:123], v[122:123], v[170:171]
	global_store_dwordx4 v244, v[120:123], s[20:21] offset:64
	global_load_dwordx4 v[168:171], v246, s[2:3] offset:128
	s_waitcnt vmcnt(20)
	v_pk_add_f32 v[124:125], v[124:125], v[172:173]
	v_pk_add_f32 v[126:127], v[126:127], v[174:175]
	global_store_dwordx4 v244, v[124:127], s[20:21] offset:96
	global_load_dwordx4 v[172:175], v246, s[2:3] offset:160
	s_waitcnt vmcnt(21)
	v_pk_add_f32 v[48:49], v[48:49], v[176:177]
	v_pk_add_f32 v[50:51], v[50:51], v[178:179]
	global_store_dwordx4 v244, v[48:51], s[20:21] offset:128
	global_load_dwordx4 v[176:179], v246, s[2:3] offset:192
	s_waitcnt vmcnt(22)
	v_pk_add_f32 v[52:53], v[52:53], v[180:181]
	v_pk_add_f32 v[54:55], v[54:55], v[182:183]
	global_store_dwordx4 v244, v[52:55], s[20:21] offset:160
	global_load_dwordx4 v[180:183], v246, s[2:3] offset:224
	s_waitcnt vmcnt(23)
	v_pk_add_f32 v[56:57], v[56:57], v[186:187]
	v_pk_add_f32 v[58:59], v[58:59], v[188:189]
	global_store_dwordx4 v244, v[56:59], s[20:21] offset:192
	global_load_dwordx4 v[186:189], v247, s[2:3]
	s_waitcnt vmcnt(24)
	v_pk_add_f32 v[60:61], v[60:61], v[192:193]
	v_pk_add_f32 v[62:63], v[62:63], v[194:195]
	global_store_dwordx4 v244, v[60:63], s[20:21] offset:224
	global_load_dwordx4 v[192:195], v247, s[2:3] offset:32
	s_waitcnt vmcnt(25)
	v_pk_add_f32 v[96:97], v[96:97], v[200:201]
	v_pk_add_f32 v[98:99], v[98:99], v[202:203]
	global_store_dwordx4 v245, v[96:99], s[20:21]
	global_load_dwordx4 v[200:203], v247, s[2:3] offset:64
	s_waitcnt vmcnt(26)
	v_pk_add_f32 v[100:101], v[100:101], v[208:209]
	v_pk_add_f32 v[102:103], v[102:103], v[210:211]
	global_store_dwordx4 v245, v[100:103], s[20:21] offset:32
	global_load_dwordx4 v[208:211], v247, s[2:3] offset:96
	s_waitcnt vmcnt(27)
;   DI void operator()(const f32x16 (&acc)[2][4], int mbase, int nbase, int l32, int g) const {
; #pragma unroll
;     for (int nb = 0; nb < 2; ++nb)
; #pragma unroll
;       for (int mb = 0; mb < 4; ++mb) {
;         const size_t tok = mbase + 32 * mb + l32;
; #pragma unroll
;         for (int j = 0; j < 4; ++j) {
;           const int n = nbase + 32 * nb + 8 * j + 4 * g;
;           f32x4 r = *(const f32x4*)(R + tok * D + n);
;           r[0] += acc[nb][mb][4 * j]; r[1] += acc[nb][mb][4 * j + 1]; r[2] += acc[nb][mb][4 * j + 2]; r[3] += acc[nb][mb][4 * j + 3];
;           *(f32x4*)(O + tok * D + n) = r;
;         }
	v_pk_add_f32 v[104:105], v[104:105], v[212:213]
	v_pk_add_f32 v[106:107], v[106:107], v[214:215]
	global_store_dwordx4 v245, v[104:107], s[20:21] offset:64
	global_load_dwordx4 v[212:215], v247, s[2:3] offset:128
	s_waitcnt vmcnt(28)
	v_pk_add_f32 v[108:109], v[108:109], v[216:217]
	v_pk_add_f32 v[110:111], v[110:111], v[218:219]
	global_store_dwordx4 v245, v[108:111], s[20:21] offset:96
	global_load_dwordx4 v[216:219], v247, s[2:3] offset:160
	s_waitcnt vmcnt(29)
	v_pk_add_f32 v[32:33], v[32:33], v[220:221]
	v_pk_add_f32 v[34:35], v[34:35], v[222:223]
	global_store_dwordx4 v245, v[32:35], s[20:21] offset:128
	global_load_dwordx4 v[220:223], v247, s[2:3] offset:192
	s_waitcnt vmcnt(30)
	v_pk_add_f32 v[36:37], v[36:37], v[224:225]
	v_pk_add_f32 v[38:39], v[38:39], v[226:227]
	global_store_dwordx4 v245, v[36:39], s[20:21] offset:160
	global_load_dwordx4 v[224:227], v247, s[2:3] offset:224
	s_waitcnt vmcnt(31)
	v_pk_add_f32 v[40:41], v[40:41], v[228:229]
	v_pk_add_f32 v[42:43], v[42:43], v[230:231]
	global_store_dwordx4 v245, v[40:43], s[20:21] offset:192
	s_waitcnt vmcnt(31)
	v_pk_add_f32 v[44:45], v[44:45], v[232:233]
	v_pk_add_f32 v[46:47], v[46:47], v[234:235]
	global_store_dwordx4 v245, v[44:47], s[20:21] offset:224
	s_waitcnt vmcnt(31)
	v_pk_add_f32 v[80:81], v[80:81], v[236:237]
	v_pk_add_f32 v[82:83], v[82:83], v[238:239]
	global_store_dwordx4 v246, v[80:83], s[20:21]
	s_waitcnt vmcnt(31)
	v_pk_add_f32 v[84:85], v[84:85], v[240:241]
	v_pk_add_f32 v[86:87], v[86:87], v[242:243]
	global_store_dwordx4 v246, v[84:87], s[20:21] offset:32
	s_waitcnt vmcnt(30)
	v_pk_add_f32 v[88:89], v[88:89], v[160:161]
	v_pk_add_f32 v[90:91], v[90:91], v[162:163]
	global_store_dwordx4 v246, v[88:91], s[20:21] offset:64
	s_waitcnt vmcnt(29)
	v_pk_add_f32 v[92:93], v[92:93], v[164:165]
	v_pk_add_f32 v[94:95], v[94:95], v[166:167]
	global_store_dwordx4 v246, v[92:95], s[20:21] offset:96
	s_waitcnt vmcnt(28)
	v_pk_add_f32 v[16:17], v[16:17], v[168:169]
	v_pk_add_f32 v[18:19], v[18:19], v[170:171]
	global_store_dwordx4 v246, v[16:19], s[20:21] offset:128
	s_waitcnt vmcnt(27)
	v_pk_add_f32 v[20:21], v[20:21], v[172:173]
	v_pk_add_f32 v[22:23], v[22:23], v[174:175]
	global_store_dwordx4 v246, v[20:23], s[20:21] offset:160
	s_waitcnt vmcnt(26)
	v_pk_add_f32 v[24:25], v[24:25], v[176:177]
	v_pk_add_f32 v[26:27], v[26:27], v[178:179]
	global_store_dwordx4 v246, v[24:27], s[20:21] offset:192
	s_waitcnt vmcnt(25)
	v_pk_add_f32 v[28:29], v[28:29], v[180:181]
	v_pk_add_f32 v[30:31], v[30:31], v[182:183]
	global_store_dwordx4 v246, v[28:31], s[20:21] offset:224
	s_waitcnt vmcnt(24)
	v_pk_add_f32 v[64:65], v[64:65], v[186:187]
	v_pk_add_f32 v[66:67], v[66:67], v[188:189]
	global_store_dwordx4 v247, v[64:67], s[20:21]
	s_waitcnt vmcnt(23)
	v_pk_add_f32 v[68:69], v[68:69], v[192:193]
	v_pk_add_f32 v[70:71], v[70:71], v[194:195]
	global_store_dwordx4 v247, v[68:71], s[20:21] offset:32
	s_waitcnt vmcnt(22)
	v_pk_add_f32 v[72:73], v[72:73], v[200:201]
	v_pk_add_f32 v[74:75], v[74:75], v[202:203]
	global_store_dwordx4 v247, v[72:75], s[20:21] offset:64
	s_waitcnt vmcnt(21)
	v_pk_add_f32 v[76:77], v[76:77], v[208:209]
	v_pk_add_f32 v[78:79], v[78:79], v[210:211]
	global_store_dwordx4 v247, v[76:79], s[20:21] offset:96
	s_waitcnt vmcnt(20)
	v_pk_add_f32 v[0:1], v[0:1], v[212:213]
	v_pk_add_f32 v[2:3], v[2:3], v[214:215]
	global_store_dwordx4 v247, v[0:3], s[20:21] offset:128
	s_waitcnt vmcnt(19)
	v_pk_add_f32 v[4:5], v[4:5], v[216:217]
	v_pk_add_f32 v[6:7], v[6:7], v[218:219]
	global_store_dwordx4 v247, v[4:7], s[20:21] offset:160
	s_waitcnt vmcnt(18)
	v_pk_add_f32 v[8:9], v[8:9], v[220:221]
	v_pk_add_f32 v[10:11], v[10:11], v[222:223]
	global_store_dwordx4 v247, v[8:11], s[20:21] offset:192
	s_waitcnt vmcnt(17)
	v_pk_add_f32 v[12:13], v[12:13], v[224:225]
	v_pk_add_f32 v[14:15], v[14:15], v[226:227]
	global_store_dwordx4 v247, v[12:15], s[20:21] offset:224
	s_and_b64 vcc, exec, s[6:7]
	s_cbranch_vccz .LBB0_767

;   DI void operator()(const f32x16 (&acc)[2][4], int mbase, int nbase, int l32, int g) const {
; #pragma unroll
;     for (int nb = 0; nb < 2; ++nb)
; #pragma unroll
;       for (int mb = 0; mb < 4; ++mb) {
;         const size_t tok = mbase + 32 * mb + l32;
; #pragma unroll
;         for (int j = 0; j < 4; ++j) {
;           const int n = nbase + 32 * nb + 8 * j + 4 * g;
;           f32x4 r = *(const f32x4*)(R + tok * D + n);
;           r[0] += acc[nb][mb][4 * j]; r[1] += acc[nb][mb][4 * j + 1]; r[2] += acc[nb][mb][4 * j + 2]; r[3] += acc[nb][mb][4 * j + 3];
;           *(f32x4*)(O + tok * D + n) = r;
;         }
.LBB0_1632:
	s_and_b32 s10, s9, 0xc0
	s_ashr_i32 s9, s9, 1
	s_and_b32 s9, s9, 0xffffff80
	s_add_i32 s9, s9, s36
	v_lshrrev_b32_e32 v160, 3, v190
	v_and_or_b32 v168, v190, 31, s9
	v_and_or_b32 v160, v160, 4, s10
	v_or_b32_e32 v160, s8, v160
	s_mov_b64 s[2:3], s[20:21]
	v_lshlrev_b32_e32 v168, 13, v168
	v_lshl_add_u32 v244, v160, 2, v168
	v_add_u32_e32 v245, 0x40000, v244
	v_add_u32_e32 v246, 0x80000, v244
	v_add_u32_e32 v247, 0xc0000, v244
	s_add_i32 s18, s18, s19
	s_add_i32 s24, s24, s25
	s_mov_b64 s[10:11], -1
	global_load_dwordx4 v[160:163], v244, s[2:3]
	global_load_dwordx4 v[164:167], v244, s[2:3] offset:32
	global_load_dwordx4 v[168:171], v244, s[2:3] offset:64
	global_load_dwordx4 v[172:175], v244, s[2:3] offset:96
	global_load_dwordx4 v[176:179], v244, s[2:3] offset:128
	global_load_dwordx4 v[180:183], v244, s[2:3] offset:160
	global_load_dwordx4 v[186:189], v244, s[2:3] offset:192
	global_load_dwordx4 v[192:195], v244, s[2:3] offset:224
	global_load_dwordx4 v[200:203], v245, s[2:3]
	global_load_dwordx4 v[208:211], v245, s[2:3] offset:32
	global_load_dwordx4 v[212:215], v245, s[2:3] offset:64
	global_load_dwordx4 v[216:219], v245, s[2:3] offset:96
	global_load_dwordx4 v[220:223], v245, s[2:3] offset:128
	global_load_dwordx4 v[224:227], v245, s[2:3] offset:160
	global_load_dwordx4 v[228:231], v245, s[2:3] offset:192
	global_load_dwordx4 v[232:235], v245, s[2:3] offset:224
	global_load_dwordx4 v[236:239], v246, s[2:3]
	global_load_dwordx4 v[240:243], v246, s[2:3] offset:32
	s_waitcnt vmcnt(17)
	v_pk_add_f32 v[112:113], v[112:113], v[160:161]
	v_pk_add_f32 v[114:115], v[114:115], v[162:163]
	global_store_dwordx4 v244, v[112:115], s[20:21]
	global_load_dwordx4 v[160:163], v246, s[2:3] offset:64
	s_waitcnt vmcnt(18)
	v_pk_add_f32 v[116:117], v[116:117], v[164:165]
	v_pk_add_f32 v[118:119], v[118:119], v[166:167]
	global_store_dwordx4 v244, v[116:119], s[20:21] offset:32
	global_load_dwordx4 v[164:167], v246, s[2:3] offset:96
	s_waitcnt vmcnt(19)
	v_pk_add_f32 v[120:121], v[120:121], v[168:169]
	v_pk_add_f32 v[122:123], v[122:123], v[170:171]
	global_store_dwordx4 v244, v[120:123], s[20:21] offset:64
	global_load_dwordx4 v[168:171], v246, s[2:3] offset:128
	s_waitcnt vmcnt(20)
	v_pk_add_f32 v[124:125], v[124:125], v[172:173]
	v_pk_add_f32 v[126:127], v[126:127], v[174:175]
	global_store_dwordx4 v244, v[124:127], s[20:21] offset:96
	global_load_dwordx4 v[172:175], v246, s[2:3] offset:160
	s_waitcnt vmcnt(21)
	v_pk_add_f32 v[48:49], v[48:49], v[176:177]
	v_pk_add_f32 v[50:51], v[50:51], v[178:179]
	global_store_dwordx4 v244, v[48:51], s[20:21] offset:128
	global_load_dwordx4 v[176:179], v246, s[2:3] offset:192
	s_waitcnt vmcnt(22)
	v_pk_add_f32 v[52:53], v[52:53], v[180:181]
	v_pk_add_f32 v[54:55], v[54:55], v[182:183]
	global_store_dwordx4 v244, v[52:55], s[20:21] offset:160
	global_load_dwordx4 v[180:183], v246, s[2:3] offset:224
	s_waitcnt vmcnt(23)
	v_pk_add_f32 v[56:57], v[56:57], v[186:187]
	v_pk_add_f32 v[58:59], v[58:59], v[188:189]
	global_store_dwordx4 v244, v[56:59], s[20:21] offset:192
	global_load_dwordx4 v[186:189], v247, s[2:3]
	s_waitcnt vmcnt(24)
	v_pk_add_f32 v[60:61], v[60:61], v[192:193]
	v_pk_add_f32 v[62:63], v[62:63], v[194:195]
	global_store_dwordx4 v244, v[60:63], s[20:21] offset:224
	global_load_dwordx4 v[192:195], v247, s[2:3] offset:32
	s_waitcnt vmcnt(25)
	v_pk_add_f32 v[96:97], v[96:97], v[200:201]
	v_pk_add_f32 v[98:99], v[98:99], v[202:203]
	global_store_dwordx4 v245, v[96:99], s[20:21]
	global_load_dwordx4 v[200:203], v247, s[2:3] offset:64
	s_waitcnt vmcnt(26)
	v_pk_add_f32 v[100:101], v[100:101], v[208:209]
	v_pk_add_f32 v[102:103], v[102:103], v[210:211]
	global_store_dwordx4 v245, v[100:103], s[20:21] offset:32
	global_load_dwordx4 v[208:211], v247, s[2:3] offset:96
	s_waitcnt vmcnt(27)
;   DI void operator()(const f32x16 (&acc)[2][4], int mbase, int nbase, int l32, int g) const {
; #pragma unroll
;     for (int nb = 0; nb < 2; ++nb)
; #pragma unroll
;       for (int mb = 0; mb < 4; ++mb) {
;         const size_t tok = mbase + 32 * mb + l32;
; #pragma unroll
;         for (int j = 0; j < 4; ++j) {
;           const int n = nbase + 32 * nb + 8 * j + 4 * g;
;           f32x4 r = *(const f32x4*)(R + tok * D + n);
;           r[0] += acc[nb][mb][4 * j]; r[1] += acc[nb][mb][4 * j + 1]; r[2] += acc[nb][mb][4 * j + 2]; r[3] += acc[nb][mb][4 * j + 3];
;           *(f32x4*)(O + tok * D + n) = r;
;         }
	v_pk_add_f32 v[104:105], v[104:105], v[212:213]
	v_pk_add_f32 v[106:107], v[106:107], v[214:215]
	global_store_dwordx4 v245, v[104:107], s[20:21] offset:64
	global_load_dwordx4 v[212:215], v247, s[2:3] offset:128
	s_waitcnt vmcnt(28)
	v_pk_add_f32 v[108:109], v[108:109], v[216:217]
	v_pk_add_f32 v[110:111], v[110:111], v[218:219]
	global_store_dwordx4 v245, v[108:111], s[20:21] offset:96
	global_load_dwordx4 v[216:219], v247, s[2:3] offset:160
	s_waitcnt vmcnt(29)
	v_pk_add_f32 v[32:33], v[32:33], v[220:221]
	v_pk_add_f32 v[34:35], v[34:35], v[222:223]
	global_store_dwordx4 v245, v[32:35], s[20:21] offset:128
	global_load_dwordx4 v[220:223], v247, s[2:3] offset:192
	s_waitcnt vmcnt(30)
	v_pk_add_f32 v[36:37], v[36:37], v[224:225]
	v_pk_add_f32 v[38:39], v[38:39], v[226:227]
	global_store_dwordx4 v245, v[36:39], s[20:21] offset:160
	global_load_dwordx4 v[224:227], v247, s[2:3] offset:224
	s_waitcnt vmcnt(31)
	v_pk_add_f32 v[40:41], v[40:41], v[228:229]
	v_pk_add_f32 v[42:43], v[42:43], v[230:231]
	global_store_dwordx4 v245, v[40:43], s[20:21] offset:192
	s_waitcnt vmcnt(31)
	v_pk_add_f32 v[44:45], v[44:45], v[232:233]
	v_pk_add_f32 v[46:47], v[46:47], v[234:235]
	global_store_dwordx4 v245, v[44:47], s[20:21] offset:224
	s_waitcnt vmcnt(31)
	v_pk_add_f32 v[80:81], v[80:81], v[236:237]
	v_pk_add_f32 v[82:83], v[82:83], v[238:239]
	global_store_dwordx4 v246, v[80:83], s[20:21]
	s_waitcnt vmcnt(31)
	v_pk_add_f32 v[84:85], v[84:85], v[240:241]
	v_pk_add_f32 v[86:87], v[86:87], v[242:243]
	global_store_dwordx4 v246, v[84:87], s[20:21] offset:32
	s_waitcnt vmcnt(30)
	v_pk_add_f32 v[88:89], v[88:89], v[160:161]
	v_pk_add_f32 v[90:91], v[90:91], v[162:163]
	global_store_dwordx4 v246, v[88:91], s[20:21] offset:64
	s_waitcnt vmcnt(29)
	v_pk_add_f32 v[92:93], v[92:93], v[164:165]
	v_pk_add_f32 v[94:95], v[94:95], v[166:167]
	global_store_dwordx4 v246, v[92:95], s[20:21] offset:96
	s_waitcnt vmcnt(28)
	v_pk_add_f32 v[16:17], v[16:17], v[168:169]
	v_pk_add_f32 v[18:19], v[18:19], v[170:171]
	global_store_dwordx4 v246, v[16:19], s[20:21] offset:128
	s_waitcnt vmcnt(27)
	v_pk_add_f32 v[20:21], v[20:21], v[172:173]
	v_pk_add_f32 v[22:23], v[22:23], v[174:175]
	global_store_dwordx4 v246, v[20:23], s[20:21] offset:160
	s_waitcnt vmcnt(26)
	v_pk_add_f32 v[24:25], v[24:25], v[176:177]
	v_pk_add_f32 v[26:27], v[26:27], v[178:179]
	global_store_dwordx4 v246, v[24:27], s[20:21] offset:192
	s_waitcnt vmcnt(25)
	v_pk_add_f32 v[28:29], v[28:29], v[180:181]
	v_pk_add_f32 v[30:31], v[30:31], v[182:183]
	global_store_dwordx4 v246, v[28:31], s[20:21] offset:224
	s_waitcnt vmcnt(24)
	v_pk_add_f32 v[64:65], v[64:65], v[186:187]
	v_pk_add_f32 v[66:67], v[66:67], v[188:189]
	global_store_dwordx4 v247, v[64:67], s[20:21]
	s_waitcnt vmcnt(23)
	v_pk_add_f32 v[68:69], v[68:69], v[192:193]
	v_pk_add_f32 v[70:71], v[70:71], v[194:195]
	global_store_dwordx4 v247, v[68:71], s[20:21] offset:32
	s_waitcnt vmcnt(22)
	v_pk_add_f32 v[72:73], v[72:73], v[200:201]
	v_pk_add_f32 v[74:75], v[74:75], v[202:203]
	global_store_dwordx4 v247, v[72:75], s[20:21] offset:64
	s_waitcnt vmcnt(21)
	v_pk_add_f32 v[76:77], v[76:77], v[208:209]
	v_pk_add_f32 v[78:79], v[78:79], v[210:211]
	global_store_dwordx4 v247, v[76:79], s[20:21] offset:96
	s_waitcnt vmcnt(20)
	v_pk_add_f32 v[0:1], v[0:1], v[212:213]
	v_pk_add_f32 v[2:3], v[2:3], v[214:215]
	global_store_dwordx4 v247, v[0:3], s[20:21] offset:128
	s_waitcnt vmcnt(19)
	v_pk_add_f32 v[4:5], v[4:5], v[216:217]
	v_pk_add_f32 v[6:7], v[6:7], v[218:219]
	global_store_dwordx4 v247, v[4:7], s[20:21] offset:160
	s_waitcnt vmcnt(18)
	v_pk_add_f32 v[8:9], v[8:9], v[220:221]
	v_pk_add_f32 v[10:11], v[10:11], v[222:223]
	global_store_dwordx4 v247, v[8:11], s[20:21] offset:192
	s_waitcnt vmcnt(17)
	v_pk_add_f32 v[12:13], v[12:13], v[224:225]
	v_pk_add_f32 v[14:15], v[14:15], v[226:227]
	global_store_dwordx4 v247, v[12:15], s[20:21] offset:224
	s_and_b64 vcc, exec, s[4:5]
	s_cbranch_vccz .LBB0_1655
